# P2 idle-time conversion chunks de-serialised: all 16 loads of a chunk issued up front, counted waits (was 4 or 8 load->wait->store round trips)
# speedup vs baseline: 1.0011x; 1.0011x over previous
; DEV unsigned pk2(float lo, float hi) { f32x2_t v = {lo, hi}; bf16x2_t b = __builtin_convertvector(v, bf16x2_t); return __builtin_bit_cast(unsigned, b); }
; __global__ void __launch_bounds__(512) mega(Params P) {
;     ...
;     for (;;) {
;       __syncthreads();
;       if (tid == 0) hs[8] = (int)atomicAdd(ctr2, 1u);
;       __syncthreads();
;       const int c = hs[8];
;       if (c >= 2560) break;
;       if (c < 2048) {
;         const int t = c >> 9; const size_t off = (size_t)(c & 511) * 32768;
;         const float* src = ((t & 1) ? P.peer_v : P.peer_u) + (size_t)(t >> 1) * 16384 * 1024 + off;
;         unsigned char* dst = ws + WS_TAB + (size_t)t * 16 * MB + off;
; #pragma unroll
;         for (int it = 0; it < 4; ++it) {
;           const size_t i = (size_t)(it * 512 + tid) * 16;
;           u32x4 o;
; #pragma unroll
;           for (int q = 0; q < 4; ++q) {
;             const f32x4 a = *(const f32x4*)(src + i + 4 * q);
;             int d = __builtin_amdgcn_cvt_pk_fp8_f32(a[0] * 64.f, a[1] * 64.f, 0, false);
;             d = __builtin_amdgcn_cvt_pk_fp8_f32(a[2] * 64.f, a[3] * 64.f, d, true);
;             o[q] = (unsigned)d;
;           }
;           *(u32x4*)(dst + i) = o;
;         }
;       } else {
;         const size_t off = (size_t)(c - 2048) * 32768;
;         const float* src = P.p + off; bf16_t* dst = (bf16_t*)(ws + WS_PB) + off;
; #pragma unroll
;         for (int it = 0; it < 8; ++it) {
;           const size_t i = (size_t)(it * 512 + tid) * 8;
;           const f32x4 a = *(const f32x4*)(src + i), b2 = *(const f32x4*)(src + i + 4);
;           u32x4 o; o[0] = pk2(a[0], a[1]); o[1] = pk2(a[2], a[3]); o[2] = pk2(b2[0], b2[1]); o[3] = pk2(b2[2], b2[3]);
;           *(u32x4*)(dst + i) = o;
;         }
.LBB0_204:
	s_or_b64 exec, exec, s[16:17]
	s_waitcnt lgkmcnt(0)
	s_barrier
	ds_read_b32 v0, v8
	s_mov_b64 s[16:17], -1
	s_waitcnt lgkmcnt(0)
	v_cmp_lt_i32_e32 vcc, s30, v0
	v_readfirstlane_b32 s20, v0
	s_cbranch_vccnz .LBB0_199
	s_cmpk_gt_i32 s20, 0x7ff
	s_cbranch_scc0 .LBB0_207
	s_add_i32 s2, s20, 0xfffff800
	s_lshl_b64 s[16:17], s[2:3], 17
	s_add_u32 s18, s54, s16
	s_addc_u32 s19, s55, s17
	s_lshl_b64 s[16:17], s[2:3], 16
	s_add_u32 s16, s22, s16
	s_addc_u32 s17, s23, s17
	global_load_dwordx4 v[16:19], v4, s[18:19]
	global_load_dwordx4 v[20:23], v4, s[18:19] offset:16
	s_add_u32 s18, s18, 0x4000
	s_addc_u32 s19, s19, 0
	global_load_dwordx4 v[44:47], v4, s[18:19]
	global_load_dwordx4 v[48:51], v4, s[18:19] offset:16
	s_add_u32 s18, s18, 0x4000
	s_addc_u32 s19, s19, 0
	global_load_dwordx4 v[52:55], v4, s[18:19]
	global_load_dwordx4 v[56:59], v4, s[18:19] offset:16
	s_add_u32 s18, s18, 0x4000
	s_addc_u32 s19, s19, 0
	global_load_dwordx4 v[60:63], v4, s[18:19]
	global_load_dwordx4 v[64:67], v4, s[18:19] offset:16
	s_add_u32 s18, s18, 0x4000
	s_addc_u32 s19, s19, 0
	global_load_dwordx4 v[68:71], v4, s[18:19]
	global_load_dwordx4 v[72:75], v4, s[18:19] offset:16
	s_add_u32 s18, s18, 0x4000
	s_addc_u32 s19, s19, 0
	global_load_dwordx4 v[76:79], v4, s[18:19]
	global_load_dwordx4 v[80:83], v4, s[18:19] offset:16
	s_add_u32 s18, s18, 0x4000
	s_addc_u32 s19, s19, 0
	global_load_dwordx4 v[84:87], v4, s[18:19]
	global_load_dwordx4 v[88:91], v4, s[18:19] offset:16
	s_add_u32 s18, s18, 0x4000
	s_addc_u32 s19, s19, 0
	global_load_dwordx4 v[92:95], v4, s[18:19]
	global_load_dwordx4 v[96:99], v4, s[18:19] offset:16
	s_waitcnt vmcnt(14)
	v_cvt_pk_bf16_f32 v24, v16, v17
	v_cvt_pk_bf16_f32 v25, v18, v19
	v_cvt_pk_bf16_f32 v26, v20, v21
	v_cvt_pk_bf16_f32 v27, v22, v23
	global_store_dwordx4 v6, v[24:27], s[16:17]
	s_add_u32 s16, s16, 0x2000
	s_addc_u32 s17, s17, 0
	s_waitcnt vmcnt(13)
	v_cvt_pk_bf16_f32 v28, v44, v45
	v_cvt_pk_bf16_f32 v29, v46, v47
	v_cvt_pk_bf16_f32 v30, v48, v49
	v_cvt_pk_bf16_f32 v31, v50, v51
	global_store_dwordx4 v6, v[28:31], s[16:17]
	s_add_u32 s16, s16, 0x2000
	s_addc_u32 s17, s17, 0
	s_waitcnt vmcnt(12)
	v_cvt_pk_bf16_f32 v24, v52, v53
	v_cvt_pk_bf16_f32 v25, v54, v55
	v_cvt_pk_bf16_f32 v26, v56, v57
	v_cvt_pk_bf16_f32 v27, v58, v59
	global_store_dwordx4 v6, v[24:27], s[16:17]
	s_add_u32 s16, s16, 0x2000
	s_addc_u32 s17, s17, 0
	s_waitcnt vmcnt(11)
	v_cvt_pk_bf16_f32 v28, v60, v61
	v_cvt_pk_bf16_f32 v29, v62, v63
	v_cvt_pk_bf16_f32 v30, v64, v65
	v_cvt_pk_bf16_f32 v31, v66, v67
	global_store_dwordx4 v6, v[28:31], s[16:17]
	s_add_u32 s16, s16, 0x2000
	s_addc_u32 s17, s17, 0
	s_waitcnt vmcnt(10)
	v_cvt_pk_bf16_f32 v24, v68, v69
	v_cvt_pk_bf16_f32 v25, v70, v71
	v_cvt_pk_bf16_f32 v26, v72, v73
	v_cvt_pk_bf16_f32 v27, v74, v75
	global_store_dwordx4 v6, v[24:27], s[16:17]
	s_add_u32 s16, s16, 0x2000
	s_addc_u32 s17, s17, 0
	s_waitcnt vmcnt(9)
	v_cvt_pk_bf16_f32 v28, v76, v77
	v_cvt_pk_bf16_f32 v29, v78, v79
	v_cvt_pk_bf16_f32 v30, v80, v81
	v_cvt_pk_bf16_f32 v31, v82, v83
	global_store_dwordx4 v6, v[28:31], s[16:17]
	s_add_u32 s16, s16, 0x2000
	s_addc_u32 s17, s17, 0
	s_waitcnt vmcnt(8)
	v_cvt_pk_bf16_f32 v24, v84, v85
	v_cvt_pk_bf16_f32 v25, v86, v87
	v_cvt_pk_bf16_f32 v26, v88, v89
	v_cvt_pk_bf16_f32 v27, v90, v91
	global_store_dwordx4 v6, v[24:27], s[16:17]
	s_add_u32 s16, s16, 0x2000
	s_addc_u32 s17, s17, 0
	s_waitcnt vmcnt(7)
	v_cvt_pk_bf16_f32 v28, v92, v93
	v_cvt_pk_bf16_f32 v29, v94, v95
	v_cvt_pk_bf16_f32 v30, v96, v97
	v_cvt_pk_bf16_f32 v31, v98, v99
	global_store_dwordx4 v6, v[28:31], s[16:17]
	s_mov_b64 s[16:17], 0
; __global__ void __launch_bounds__(512) mega(Params P) {
;     ...
;       if (c < 2048) {
;         const int t = c >> 9; const size_t off = (size_t)(c & 511) * 32768;
;         const float* src = ((t & 1) ? P.peer_v : P.peer_u) + (size_t)(t >> 1) * 16384 * 1024 + off;
;         unsigned char* dst = ws + WS_TAB + (size_t)t * 16 * MB + off;
; #pragma unroll
;         for (int it = 0; it < 4; ++it) {
;           const size_t i = (size_t)(it * 512 + tid) * 16;
;           u32x4 o;
; #pragma unroll
;           for (int q = 0; q < 4; ++q) {
;             const f32x4 a = *(const f32x4*)(src + i + 4 * q);
;             int d = __builtin_amdgcn_cvt_pk_fp8_f32(a[0] * 64.f, a[1] * 64.f, 0, false);
;             d = __builtin_amdgcn_cvt_pk_fp8_f32(a[2] * 64.f, a[3] * 64.f, d, true);
;             o[q] = (unsigned)d;
;           }
;           *(u32x4*)(dst + i) = o;
;         }
.LBB0_207:
	s_andn2_b64 vcc, exec, s[16:17]
	s_cbranch_vccnz .LBB0_198
	s_lshl_b32 s2, s20, 15
	s_ashr_i32 s18, s20, 9
	s_and_b32 s2, s2, 0xff8000
	v_readlane_b32 s36, v232, 21
	s_bitcmp0_b32 s20, 9
	v_readlane_b32 s48, v232, 33
	v_readlane_b32 s49, v232, 34
	v_readlane_b32 s50, v232, 35
	v_readlane_b32 s51, v232, 36
	s_cselect_b32 s19, s49, s51
	s_cselect_b32 s21, s48, s50
	s_ashr_i32 s16, s20, 10
	s_ashr_i32 s17, s16, 31
	s_lshl_b64 s[16:17], s[16:17], 26
	s_add_u32 s16, s21, s16
	s_addc_u32 s17, s19, s17
	s_lshl_b32 s19, s2, 2
	s_add_u32 s16, s16, s19
	s_addc_u32 s17, s17, 0
	v_lshlrev_b32_e32 v0, 2, v178
	global_load_dwordx4 v[16:19], v0, s[16:17]
	global_load_dwordx4 v[20:23], v0, s[16:17] offset:16
	global_load_dwordx4 v[24:27], v0, s[16:17] offset:32
	global_load_dwordx4 v[28:31], v0, s[16:17] offset:48
	s_add_u32 s16, s16, 0x8000
	s_addc_u32 s17, s17, 0
	global_load_dwordx4 v[44:47], v0, s[16:17]
	global_load_dwordx4 v[48:51], v0, s[16:17] offset:16
	global_load_dwordx4 v[52:55], v0, s[16:17] offset:32
	global_load_dwordx4 v[56:59], v0, s[16:17] offset:48
	s_add_u32 s16, s16, 0x8000
	s_addc_u32 s17, s17, 0
	global_load_dwordx4 v[60:63], v0, s[16:17]
	global_load_dwordx4 v[64:67], v0, s[16:17] offset:16
	global_load_dwordx4 v[68:71], v0, s[16:17] offset:32
	global_load_dwordx4 v[72:75], v0, s[16:17] offset:48
	s_add_u32 s16, s16, 0x8000
	s_addc_u32 s17, s17, 0
	global_load_dwordx4 v[76:79], v0, s[16:17]
	global_load_dwordx4 v[80:83], v0, s[16:17] offset:16
	global_load_dwordx4 v[84:87], v0, s[16:17] offset:32
	global_load_dwordx4 v[88:91], v0, s[16:17] offset:48
	s_ashr_i32 s19, s18, 31
	s_lshl_b64 s[18:19], s[18:19], 24
	s_add_u32 s18, s24, s18
	s_addc_u32 s19, s25, s19
	s_lshr_b32 s99, s2, 3
	s_add_u32 s100, s18, s99
	s_addc_u32 s101, s19, 0
	v_bfe_u32 v250, v178, 7, 3
	v_lshlrev_b32_e32 v250, 21, v250
	v_lshrrev_b32_e32 v251, 10, v178
	v_lshl_or_b32 v250, v251, 7, v250
	v_bfe_u32 v251, v178, 4, 3
	v_lshl_or_b32 v250, v251, 4, v250
	v_mov_b32_e32 v251, 0
	v_lshl_add_u64 v[254:255], s[100:101], 0, v[250:251]
	v_readlane_b32 s37, v232, 22
	v_readlane_b32 s38, v232, 23
	v_readlane_b32 s39, v232, 24
	v_readlane_b32 s40, v232, 25
	v_readlane_b32 s41, v232, 26
	v_readlane_b32 s42, v232, 27
	v_readlane_b32 s43, v232, 28
	v_readlane_b32 s44, v232, 29
	v_readlane_b32 s45, v232, 30
	v_readlane_b32 s46, v232, 31
	v_readlane_b32 s47, v232, 32
	s_waitcnt vmcnt(12)
	v_mov_b32_e32 v32, v1
	v_mov_b32_e32 v33, v1
	v_mov_b32_e32 v34, v1
	v_mov_b32_e32 v35, v1
	v_mul_f32_e32 v16, 0x42800000, v16
	v_mul_f32_e32 v17, 0x42800000, v17
	v_mul_f32_e32 v18, 0x42800000, v18
	v_mul_f32_e32 v19, 0x42800000, v19
	v_mul_f32_e32 v20, 0x42800000, v20
	v_mul_f32_e32 v21, 0x42800000, v21
	v_mul_f32_e32 v22, 0x42800000, v22
	v_mul_f32_e32 v23, 0x42800000, v23
	v_mul_f32_e32 v24, 0x42800000, v24
	v_mul_f32_e32 v25, 0x42800000, v25
	v_mul_f32_e32 v26, 0x42800000, v26
	v_mul_f32_e32 v27, 0x42800000, v27
	v_mul_f32_e32 v28, 0x42800000, v28
	v_mul_f32_e32 v29, 0x42800000, v29
	v_mul_f32_e32 v30, 0x42800000, v30
	v_mul_f32_e32 v31, 0x42800000, v31
	v_cvt_pk_fp8_f32 v32, v16, v17
	v_cvt_pk_fp8_f32 v33, v20, v21
	v_cvt_pk_fp8_f32 v34, v24, v25
	v_cvt_pk_fp8_f32 v35, v28, v29
	v_cvt_pk_fp8_f32 v32, v18, v19 op_sel:[0,0,1]
	v_cvt_pk_fp8_f32 v33, v22, v23 op_sel:[0,0,1]
	v_cvt_pk_fp8_f32 v34, v26, v27 op_sel:[0,0,1]
	v_cvt_pk_fp8_f32 v35, v30, v31 op_sel:[0,0,1]
	global_store_dwordx4 v[254:255], v[32:35], off
	s_waitcnt vmcnt(9)
	v_mov_b32_e32 v36, v1
	v_mov_b32_e32 v37, v1
	v_mov_b32_e32 v38, v1
	v_mov_b32_e32 v39, v1
	v_mul_f32_e32 v44, 0x42800000, v44
	v_mul_f32_e32 v45, 0x42800000, v45
	v_mul_f32_e32 v46, 0x42800000, v46
	v_mul_f32_e32 v47, 0x42800000, v47
	v_mul_f32_e32 v48, 0x42800000, v48
	v_mul_f32_e32 v49, 0x42800000, v49
	v_mul_f32_e32 v50, 0x42800000, v50
	v_mul_f32_e32 v51, 0x42800000, v51
	v_mul_f32_e32 v52, 0x42800000, v52
	v_mul_f32_e32 v53, 0x42800000, v53
	v_mul_f32_e32 v54, 0x42800000, v54
	v_mul_f32_e32 v55, 0x42800000, v55
	v_mul_f32_e32 v56, 0x42800000, v56
	v_mul_f32_e32 v57, 0x42800000, v57
	v_mul_f32_e32 v58, 0x42800000, v58
	v_mul_f32_e32 v59, 0x42800000, v59
	v_cvt_pk_fp8_f32 v36, v44, v45
	v_cvt_pk_fp8_f32 v37, v48, v49
	v_cvt_pk_fp8_f32 v38, v52, v53
	v_cvt_pk_fp8_f32 v39, v56, v57
	v_cvt_pk_fp8_f32 v36, v46, v47 op_sel:[0,0,1]
	v_cvt_pk_fp8_f32 v37, v50, v51 op_sel:[0,0,1]
	v_cvt_pk_fp8_f32 v38, v54, v55 op_sel:[0,0,1]
	v_cvt_pk_fp8_f32 v39, v58, v59 op_sel:[0,0,1]
	global_store_dwordx4 v[254:255], v[36:39], off offset:1024
	s_waitcnt vmcnt(6)
	v_mov_b32_e32 v32, v1
	v_mov_b32_e32 v33, v1
	v_mov_b32_e32 v34, v1
	v_mov_b32_e32 v35, v1
	v_mul_f32_e32 v60, 0x42800000, v60
	v_mul_f32_e32 v61, 0x42800000, v61
	v_mul_f32_e32 v62, 0x42800000, v62
	v_mul_f32_e32 v63, 0x42800000, v63
	v_mul_f32_e32 v64, 0x42800000, v64
	v_mul_f32_e32 v65, 0x42800000, v65
	v_mul_f32_e32 v66, 0x42800000, v66
	v_mul_f32_e32 v67, 0x42800000, v67
	v_mul_f32_e32 v68, 0x42800000, v68
	v_mul_f32_e32 v69, 0x42800000, v69
	v_mul_f32_e32 v70, 0x42800000, v70
	v_mul_f32_e32 v71, 0x42800000, v71
	v_mul_f32_e32 v72, 0x42800000, v72
	v_mul_f32_e32 v73, 0x42800000, v73
	v_mul_f32_e32 v74, 0x42800000, v74
	v_mul_f32_e32 v75, 0x42800000, v75
	v_cvt_pk_fp8_f32 v32, v60, v61
	v_cvt_pk_fp8_f32 v33, v64, v65
	v_cvt_pk_fp8_f32 v34, v68, v69
	v_cvt_pk_fp8_f32 v35, v72, v73
	v_cvt_pk_fp8_f32 v32, v62, v63 op_sel:[0,0,1]
	v_cvt_pk_fp8_f32 v33, v66, v67 op_sel:[0,0,1]
	v_cvt_pk_fp8_f32 v34, v70, v71 op_sel:[0,0,1]
	v_cvt_pk_fp8_f32 v35, v74, v75 op_sel:[0,0,1]
	global_store_dwordx4 v[254:255], v[32:35], off offset:2048
	s_waitcnt vmcnt(3)
	v_mov_b32_e32 v36, v1
	v_mov_b32_e32 v37, v1
	v_mov_b32_e32 v38, v1
	v_mov_b32_e32 v39, v1
	v_mul_f32_e32 v76, 0x42800000, v76
	v_mul_f32_e32 v77, 0x42800000, v77
	v_mul_f32_e32 v78, 0x42800000, v78
	v_mul_f32_e32 v79, 0x42800000, v79
	v_mul_f32_e32 v80, 0x42800000, v80
	v_mul_f32_e32 v81, 0x42800000, v81
	v_mul_f32_e32 v82, 0x42800000, v82
	v_mul_f32_e32 v83, 0x42800000, v83
	v_mul_f32_e32 v84, 0x42800000, v84
	v_mul_f32_e32 v85, 0x42800000, v85
	v_mul_f32_e32 v86, 0x42800000, v86
	v_mul_f32_e32 v87, 0x42800000, v87
	v_mul_f32_e32 v88, 0x42800000, v88
	v_mul_f32_e32 v89, 0x42800000, v89
	v_mul_f32_e32 v90, 0x42800000, v90
	v_mul_f32_e32 v91, 0x42800000, v91
	v_cvt_pk_fp8_f32 v36, v76, v77
	v_cvt_pk_fp8_f32 v37, v80, v81
	v_cvt_pk_fp8_f32 v38, v84, v85
	v_cvt_pk_fp8_f32 v39, v88, v89
	v_cvt_pk_fp8_f32 v36, v78, v79 op_sel:[0,0,1]
	v_cvt_pk_fp8_f32 v37, v82, v83 op_sel:[0,0,1]
	v_cvt_pk_fp8_f32 v38, v86, v87 op_sel:[0,0,1]
	v_cvt_pk_fp8_f32 v39, v90, v91 op_sel:[0,0,1]
	global_store_dwordx4 v[254:255], v[36:39], off offset:3072
	s_branch .LBB0_198
